# s6 layer-0 xb stores: 2x8-B paired into 16-B via v_permlane16_swap (on top of s3w)
# speedup vs baseline: 1.0145x; 1.0047x over previous
.LBB0_363:
	s_or_b64 exec, exec, s[4:5]
	v_lshlrev_b32_e32 v32, 3, v192
	s_waitcnt lgkmcnt(0)
	s_barrier
	v_bfe_u32 v228, v210, 4, 1
	v_mul_u32_u24_e32 v228, 24, v228
	v_mov_b32_e32 v229, 0
	ds_read_b64 v[192:193], v32 offset:8192
	v_lshlrev_b64 v[32:33], 10, v[162:163]
	v_lshl_add_u64 v[194:195], v[32:33], 0, v[160:161]
	v_readlane_b32 s4, v254, 1
	v_readlane_b32 s10, v254, 7
	s_waitcnt lgkmcnt(0)
	v_sub_f32_e32 v33, v159, v192
	v_sub_f32_e32 v32, v158, v192
	v_sub_f32_e32 v35, v157, v192
	v_sub_f32_e32 v34, v156, v192
	v_pk_mul_f32 v[156:157], v[192:193], v[34:35] op_sel:[1,0]
	v_pk_mul_f32 v[32:33], v[192:193], v[32:33] op_sel:[1,0]
	v_readlane_b32 s11, v254, 8
	v_mov_b32_e32 v162, v193
	v_mov_b32_e32 v163, v193
	v_pk_fma_f32 v[34:35], v[26:27], v[32:33], v[30:31]
	v_pk_fma_f32 v[32:33], v[24:25], v[156:157], v[28:29]
	v_lshl_add_u64 v[156:157], v[194:195], 2, s[10:11]
	s_mov_b64 s[2:3], -1
	s_and_b64 vcc, exec, s[38:39]
	v_sub_f32_e32 v155, v155, v192
	v_sub_f32_e32 v154, v154, v192
	v_sub_f32_e32 v159, v153, v192
	v_sub_f32_e32 v158, v152, v192
	v_readlane_b32 s5, v254, 2
	v_readlane_b32 s6, v254, 3
	v_readlane_b32 s7, v254, 4
	v_readlane_b32 s8, v254, 5
	v_readlane_b32 s9, v254, 6
	global_store_dwordx4 v[156:157], v[32:35], off sc1
	s_cbranch_vccz .LBB0_365
	v_mov_b32_e32 v204, v193
	v_mov_b32_e32 v205, v193
	v_pk_mul_f32 v[152:153], v[162:163], v[158:159]
	v_pk_mul_f32 v[204:205], v[204:205], v[154:155]
	v_pk_fma_f32 v[220:221], v[16:17], v[152:153], v[20:21]
	v_pk_fma_f32 v[222:223], v[18:19], v[204:205], v[22:23]
	global_store_dwordx4 v[156:157], v[220:223], off offset:64 sc1
	s_mov_b64 s[2:3], 0
.LBB0_365:
	s_andn2_b64 vcc, exec, s[2:3]
	v_lshl_add_u64 v[152:153], v[194:195], 1, s[80:81]
	v_lshl_add_u64 v[152:153], v[152:153], 0, v[228:229]
	s_cbranch_vccnz .LBB0_367
	v_cvt_pk_bf16_f32 v32, v32, v33
	v_cvt_pk_bf16_f32 v33, v34, v35
	v_mov_b32_e32 v34, v193
	v_mov_b32_e32 v35, v193
	v_mov_b32_e32 v224, v32
	v_mov_b32_e32 v225, v33
	v_pk_mul_f32 v[32:33], v[162:163], v[158:159]
	v_pk_mul_f32 v[34:35], v[34:35], v[154:155]
	v_pk_fma_f32 v[32:33], v[16:17], v[32:33], v[20:21]
	v_pk_fma_f32 v[34:35], v[18:19], v[34:35], v[22:23]
	global_store_dwordx4 v[156:157], v[32:35], off offset:64 sc1
	s_nop 1
	v_cvt_pk_bf16_f32 v32, v32, v33
	v_cvt_pk_bf16_f32 v33, v34, v35
	v_mov_b32_e32 v226, v32
	v_mov_b32_e32 v227, v33
	s_nop 1
	v_permlane16_swap_b32_e32 v224, v226
	v_permlane16_swap_b32_e32 v225, v227
	s_nop 1
	global_store_dwordx4 v[152:153], v[224:227], off

.LBB0_369:
	s_andn2_b64 vcc, exec, s[2:3]
	s_cbranch_vccnz .LBB0_371
	v_cvt_pk_bf16_f32 v32, v32, v33
	v_cvt_pk_bf16_f32 v33, v34, v35
	v_mov_b32_e32 v192, v193
	v_mov_b32_e32 v224, v32
	v_mov_b32_e32 v225, v33
	v_pk_mul_f32 v[32:33], v[162:163], v[144:145]
	v_pk_mul_f32 v[34:35], v[192:193], v[146:147]
	v_pk_fma_f32 v[32:33], v[0:1], v[32:33], v[4:5]
	v_pk_fma_f32 v[34:35], v[2:3], v[34:35], v[6:7]
	global_store_dwordx4 v[156:157], v[32:35], off offset:576 sc1
	s_nop 1
	v_cvt_pk_bf16_f32 v32, v32, v33
	v_cvt_pk_bf16_f32 v33, v34, v35
	v_mov_b32_e32 v226, v32
	v_mov_b32_e32 v227, v33
	s_nop 1
	v_permlane16_swap_b32_e32 v224, v226
	v_permlane16_swap_b32_e32 v225, v227
	s_nop 1
	global_store_dwordx4 v[152:153], v[224:227], off offset:256

.LBB0_373:
	s_andn2_b64 vcc, exec, s[2:3]
	v_lshl_add_u64 v[136:137], v[148:149], 1, s[80:81]
	v_lshl_add_u64 v[136:137], v[136:137], 0, v[228:229]
	s_cbranch_vccnz .LBB0_375
	v_cvt_pk_bf16_f32 v32, v32, v33
	v_cvt_pk_bf16_f32 v33, v34, v35
	v_mov_b32_e32 v34, v145
	v_mov_b32_e32 v35, v145
	v_mov_b32_e32 v224, v32
	v_mov_b32_e32 v225, v33
	v_pk_mul_f32 v[32:33], v[146:147], v[142:143]
	v_pk_mul_f32 v[34:35], v[34:35], v[138:139]
	v_pk_fma_f32 v[32:33], v[16:17], v[32:33], v[20:21]
	v_pk_fma_f32 v[34:35], v[18:19], v[34:35], v[22:23]
	global_store_dwordx4 v[140:141], v[32:35], off offset:64 sc1
	s_nop 1
	v_cvt_pk_bf16_f32 v32, v32, v33
	v_cvt_pk_bf16_f32 v33, v34, v35
	v_mov_b32_e32 v226, v32
	v_mov_b32_e32 v227, v33
	s_nop 1
	v_permlane16_swap_b32_e32 v224, v226
	v_permlane16_swap_b32_e32 v225, v227
	s_nop 1
	global_store_dwordx4 v[136:137], v[224:227], off

.LBB0_377:
	s_andn2_b64 vcc, exec, s[2:3]
	s_cbranch_vccnz .LBB0_379
	v_cvt_pk_bf16_f32 v32, v32, v33
	v_cvt_pk_bf16_f32 v33, v34, v35
	v_mov_b32_e32 v144, v145
	v_mov_b32_e32 v224, v32
	v_mov_b32_e32 v225, v33
	v_pk_mul_f32 v[32:33], v[146:147], v[128:129]
	v_pk_mul_f32 v[34:35], v[144:145], v[130:131]
	v_pk_fma_f32 v[32:33], v[0:1], v[32:33], v[4:5]
	v_pk_fma_f32 v[34:35], v[2:3], v[34:35], v[6:7]
	global_store_dwordx4 v[140:141], v[32:35], off offset:576 sc1
	s_nop 1
	v_cvt_pk_bf16_f32 v32, v32, v33
	v_cvt_pk_bf16_f32 v33, v34, v35
	v_mov_b32_e32 v226, v32
	v_mov_b32_e32 v227, v33
	s_nop 1
	v_permlane16_swap_b32_e32 v224, v226
	v_permlane16_swap_b32_e32 v225, v227
	s_nop 1
	global_store_dwordx4 v[136:137], v[224:227], off offset:256

.LBB0_381:
	s_andn2_b64 vcc, exec, s[2:3]
	v_lshl_add_u64 v[120:121], v[132:133], 1, s[80:81]
	v_lshl_add_u64 v[120:121], v[120:121], 0, v[228:229]
	s_cbranch_vccnz .LBB0_383
	v_cvt_pk_bf16_f32 v32, v32, v33
	v_cvt_pk_bf16_f32 v33, v34, v35
	v_mov_b32_e32 v34, v129
	v_mov_b32_e32 v35, v129
	v_mov_b32_e32 v224, v32
	v_mov_b32_e32 v225, v33
	v_pk_mul_f32 v[32:33], v[130:131], v[126:127]
	v_pk_mul_f32 v[34:35], v[34:35], v[122:123]
	v_pk_fma_f32 v[32:33], v[16:17], v[32:33], v[20:21]
	v_pk_fma_f32 v[34:35], v[18:19], v[34:35], v[22:23]
	global_store_dwordx4 v[124:125], v[32:35], off offset:64 sc1
	s_nop 1
	v_cvt_pk_bf16_f32 v32, v32, v33
	v_cvt_pk_bf16_f32 v33, v34, v35
	v_mov_b32_e32 v226, v32
	v_mov_b32_e32 v227, v33
	s_nop 1
	v_permlane16_swap_b32_e32 v224, v226
	v_permlane16_swap_b32_e32 v225, v227
	s_nop 1
	global_store_dwordx4 v[120:121], v[224:227], off

.LBB0_385:
	s_andn2_b64 vcc, exec, s[2:3]
	s_cbranch_vccnz .LBB0_387
	v_cvt_pk_bf16_f32 v32, v32, v33
	v_cvt_pk_bf16_f32 v33, v34, v35
	v_mov_b32_e32 v128, v129
	v_mov_b32_e32 v224, v32
	v_mov_b32_e32 v225, v33
	v_pk_mul_f32 v[32:33], v[130:131], v[112:113]
	v_pk_mul_f32 v[34:35], v[128:129], v[114:115]
	v_pk_fma_f32 v[32:33], v[0:1], v[32:33], v[4:5]
	v_pk_fma_f32 v[34:35], v[2:3], v[34:35], v[6:7]
	global_store_dwordx4 v[124:125], v[32:35], off offset:576 sc1
	s_nop 1
	v_cvt_pk_bf16_f32 v32, v32, v33
	v_cvt_pk_bf16_f32 v33, v34, v35
	v_mov_b32_e32 v226, v32
	v_mov_b32_e32 v227, v33
	s_nop 1
	v_permlane16_swap_b32_e32 v224, v226
	v_permlane16_swap_b32_e32 v225, v227
	s_nop 1
	global_store_dwordx4 v[120:121], v[224:227], off offset:256

.LBB0_389:
	s_andn2_b64 vcc, exec, s[2:3]
	v_lshl_add_u64 v[104:105], v[116:117], 1, s[80:81]
	v_lshl_add_u64 v[104:105], v[104:105], 0, v[228:229]
	s_cbranch_vccnz .LBB0_391
	v_cvt_pk_bf16_f32 v32, v32, v33
	v_cvt_pk_bf16_f32 v33, v34, v35
	v_mov_b32_e32 v34, v113
	v_mov_b32_e32 v35, v113
	v_mov_b32_e32 v224, v32
	v_mov_b32_e32 v225, v33
	v_pk_mul_f32 v[32:33], v[114:115], v[110:111]
	v_pk_mul_f32 v[34:35], v[34:35], v[106:107]
	v_pk_fma_f32 v[32:33], v[16:17], v[32:33], v[20:21]
	v_pk_fma_f32 v[34:35], v[18:19], v[34:35], v[22:23]
	global_store_dwordx4 v[108:109], v[32:35], off offset:64 sc1
	s_nop 1
	v_cvt_pk_bf16_f32 v32, v32, v33
	v_cvt_pk_bf16_f32 v33, v34, v35
	v_mov_b32_e32 v226, v32
	v_mov_b32_e32 v227, v33
	s_nop 1
	v_permlane16_swap_b32_e32 v224, v226
	v_permlane16_swap_b32_e32 v225, v227
	s_nop 1
	global_store_dwordx4 v[104:105], v[224:227], off

.LBB0_393:
	s_andn2_b64 vcc, exec, s[2:3]
	s_cbranch_vccnz .LBB0_395
	v_cvt_pk_bf16_f32 v32, v32, v33
	v_cvt_pk_bf16_f32 v33, v34, v35
	v_mov_b32_e32 v112, v113
	v_mov_b32_e32 v224, v32
	v_mov_b32_e32 v225, v33
	v_pk_mul_f32 v[32:33], v[114:115], v[96:97]
	v_pk_mul_f32 v[34:35], v[112:113], v[98:99]
	v_pk_fma_f32 v[32:33], v[0:1], v[32:33], v[4:5]
	v_pk_fma_f32 v[34:35], v[2:3], v[34:35], v[6:7]
	global_store_dwordx4 v[108:109], v[32:35], off offset:576 sc1
	s_nop 1
	v_cvt_pk_bf16_f32 v32, v32, v33
	v_cvt_pk_bf16_f32 v33, v34, v35
	v_mov_b32_e32 v226, v32
	v_mov_b32_e32 v227, v33
	s_nop 1
	v_permlane16_swap_b32_e32 v224, v226
	v_permlane16_swap_b32_e32 v225, v227
	s_nop 1
	global_store_dwordx4 v[104:105], v[224:227], off offset:256

.LBB0_397:
	s_andn2_b64 vcc, exec, s[2:3]
	v_lshl_add_u64 v[88:89], v[100:101], 1, s[80:81]
	v_lshl_add_u64 v[88:89], v[88:89], 0, v[228:229]
	s_cbranch_vccnz .LBB0_399
	v_cvt_pk_bf16_f32 v32, v32, v33
	v_cvt_pk_bf16_f32 v33, v34, v35
	v_mov_b32_e32 v34, v97
	v_mov_b32_e32 v35, v97
	v_mov_b32_e32 v224, v32
	v_mov_b32_e32 v225, v33
	v_pk_mul_f32 v[32:33], v[98:99], v[94:95]
	v_pk_mul_f32 v[34:35], v[34:35], v[90:91]
	v_pk_fma_f32 v[32:33], v[16:17], v[32:33], v[20:21]
	v_pk_fma_f32 v[34:35], v[18:19], v[34:35], v[22:23]
	global_store_dwordx4 v[92:93], v[32:35], off offset:64 sc1
	s_nop 1
	v_cvt_pk_bf16_f32 v32, v32, v33
	v_cvt_pk_bf16_f32 v33, v34, v35
	v_mov_b32_e32 v226, v32
	v_mov_b32_e32 v227, v33
	s_nop 1
	v_permlane16_swap_b32_e32 v224, v226
	v_permlane16_swap_b32_e32 v225, v227
	s_nop 1
	global_store_dwordx4 v[88:89], v[224:227], off

.LBB0_401:
	s_andn2_b64 vcc, exec, s[2:3]
	s_cbranch_vccnz .LBB0_403
	v_cvt_pk_bf16_f32 v32, v32, v33
	v_cvt_pk_bf16_f32 v33, v34, v35
	v_mov_b32_e32 v96, v97
	v_mov_b32_e32 v224, v32
	v_mov_b32_e32 v225, v33
	v_pk_mul_f32 v[32:33], v[98:99], v[80:81]
	v_pk_mul_f32 v[34:35], v[96:97], v[82:83]
	v_pk_fma_f32 v[32:33], v[0:1], v[32:33], v[4:5]
	v_pk_fma_f32 v[34:35], v[2:3], v[34:35], v[6:7]
	global_store_dwordx4 v[92:93], v[32:35], off offset:576 sc1
	s_nop 1
	v_cvt_pk_bf16_f32 v32, v32, v33
	v_cvt_pk_bf16_f32 v33, v34, v35
	v_mov_b32_e32 v226, v32
	v_mov_b32_e32 v227, v33
	s_nop 1
	v_permlane16_swap_b32_e32 v224, v226
	v_permlane16_swap_b32_e32 v225, v227
	s_nop 1
	global_store_dwordx4 v[88:89], v[224:227], off offset:256

.LBB0_405:
	s_andn2_b64 vcc, exec, s[2:3]
	v_lshl_add_u64 v[72:73], v[84:85], 1, s[80:81]
	v_lshl_add_u64 v[72:73], v[72:73], 0, v[228:229]
	s_cbranch_vccnz .LBB0_407
	v_cvt_pk_bf16_f32 v32, v32, v33
	v_cvt_pk_bf16_f32 v33, v34, v35
	v_mov_b32_e32 v34, v81
	v_mov_b32_e32 v35, v81
	v_mov_b32_e32 v224, v32
	v_mov_b32_e32 v225, v33
	v_pk_mul_f32 v[32:33], v[82:83], v[78:79]
	v_pk_mul_f32 v[34:35], v[34:35], v[74:75]
	v_pk_fma_f32 v[32:33], v[16:17], v[32:33], v[20:21]
	v_pk_fma_f32 v[34:35], v[18:19], v[34:35], v[22:23]
	global_store_dwordx4 v[76:77], v[32:35], off offset:64 sc1
	s_nop 1
	v_cvt_pk_bf16_f32 v32, v32, v33
	v_cvt_pk_bf16_f32 v33, v34, v35
	v_mov_b32_e32 v226, v32
	v_mov_b32_e32 v227, v33
	s_nop 1
	v_permlane16_swap_b32_e32 v224, v226
	v_permlane16_swap_b32_e32 v225, v227
	s_nop 1
	global_store_dwordx4 v[72:73], v[224:227], off

.LBB0_409:
	s_andn2_b64 vcc, exec, s[2:3]
	s_cbranch_vccnz .LBB0_411
	v_cvt_pk_bf16_f32 v32, v32, v33
	v_cvt_pk_bf16_f32 v33, v34, v35
	v_mov_b32_e32 v80, v81
	v_mov_b32_e32 v224, v32
	v_mov_b32_e32 v225, v33
	v_pk_mul_f32 v[32:33], v[82:83], v[64:65]
	v_pk_mul_f32 v[34:35], v[80:81], v[66:67]
	v_pk_fma_f32 v[32:33], v[0:1], v[32:33], v[4:5]
	v_pk_fma_f32 v[34:35], v[2:3], v[34:35], v[6:7]
	global_store_dwordx4 v[76:77], v[32:35], off offset:576 sc1
	s_nop 1
	v_cvt_pk_bf16_f32 v32, v32, v33
	v_cvt_pk_bf16_f32 v33, v34, v35
	v_mov_b32_e32 v226, v32
	v_mov_b32_e32 v227, v33
	s_nop 1
	v_permlane16_swap_b32_e32 v224, v226
	v_permlane16_swap_b32_e32 v225, v227
	s_nop 1
	global_store_dwordx4 v[72:73], v[224:227], off offset:256

.LBB0_413:
	s_andn2_b64 vcc, exec, s[2:3]
	v_lshl_add_u64 v[56:57], v[68:69], 1, s[80:81]
	v_lshl_add_u64 v[56:57], v[56:57], 0, v[228:229]
	s_cbranch_vccnz .LBB0_415
	v_cvt_pk_bf16_f32 v32, v32, v33
	v_cvt_pk_bf16_f32 v33, v34, v35
	v_mov_b32_e32 v34, v65
	v_mov_b32_e32 v35, v65
	v_mov_b32_e32 v224, v32
	v_mov_b32_e32 v225, v33
	v_pk_mul_f32 v[32:33], v[66:67], v[62:63]
	v_pk_mul_f32 v[34:35], v[34:35], v[58:59]
	v_pk_fma_f32 v[32:33], v[16:17], v[32:33], v[20:21]
	v_pk_fma_f32 v[34:35], v[18:19], v[34:35], v[22:23]
	global_store_dwordx4 v[60:61], v[32:35], off offset:64 sc1
	s_nop 1
	v_cvt_pk_bf16_f32 v32, v32, v33
	v_cvt_pk_bf16_f32 v33, v34, v35
	v_mov_b32_e32 v226, v32
	v_mov_b32_e32 v227, v33
	s_nop 1
	v_permlane16_swap_b32_e32 v224, v226
	v_permlane16_swap_b32_e32 v225, v227
	s_nop 1
	global_store_dwordx4 v[56:57], v[224:227], off

.LBB0_417:
	s_andn2_b64 vcc, exec, s[2:3]
	s_cbranch_vccnz .LBB0_419
	v_cvt_pk_bf16_f32 v32, v32, v33
	v_cvt_pk_bf16_f32 v33, v34, v35
	v_mov_b32_e32 v64, v65
	v_mov_b32_e32 v224, v32
	v_mov_b32_e32 v225, v33
	v_pk_mul_f32 v[32:33], v[66:67], v[48:49]
	v_pk_mul_f32 v[34:35], v[64:65], v[50:51]
	v_pk_fma_f32 v[32:33], v[0:1], v[32:33], v[4:5]
	v_pk_fma_f32 v[34:35], v[2:3], v[34:35], v[6:7]
	global_store_dwordx4 v[60:61], v[32:35], off offset:576 sc1
	s_nop 1
	v_cvt_pk_bf16_f32 v32, v32, v33
	v_cvt_pk_bf16_f32 v33, v34, v35
	v_mov_b32_e32 v226, v32
	v_mov_b32_e32 v227, v33
	s_nop 1
	v_permlane16_swap_b32_e32 v224, v226
	v_permlane16_swap_b32_e32 v225, v227
	s_nop 1
	global_store_dwordx4 v[56:57], v[224:227], off offset:256

.LBB0_421:
	s_andn2_b64 vcc, exec, s[2:3]
	v_lshl_add_u64 v[30:31], v[48:49], 1, s[80:81]
	v_lshl_add_u64 v[30:31], v[30:31], 0, v[228:229]
	s_cbranch_vccnz .LBB0_423
	v_cvt_pk_bf16_f32 v24, v24, v25
	v_cvt_pk_bf16_f32 v25, v26, v27
	v_mov_b32_e32 v26, v33
	v_mov_b32_e32 v27, v33
	v_mov_b32_e32 v224, v24
	v_mov_b32_e32 v225, v25
	v_pk_mul_f32 v[24:25], v[34:35], v[40:41]
	v_pk_mul_f32 v[26:27], v[26:27], v[42:43]
	v_pk_fma_f32 v[16:17], v[16:17], v[24:25], v[20:21]
	v_pk_fma_f32 v[18:19], v[18:19], v[26:27], v[22:23]
	global_store_dwordx4 v[28:29], v[16:19], off offset:64 sc1
	s_nop 1
	v_cvt_pk_bf16_f32 v16, v16, v17
	v_cvt_pk_bf16_f32 v17, v18, v19
	v_mov_b32_e32 v226, v16
	v_mov_b32_e32 v227, v17
	s_nop 1
	v_permlane16_swap_b32_e32 v224, v226
	v_permlane16_swap_b32_e32 v225, v227
	s_nop 1
	global_store_dwordx4 v[30:31], v[224:227], off

.LBB0_425:
	s_andn2_b64 vcc, exec, s[2:3]
	s_cbranch_vccnz .LBB0_427
	v_cvt_pk_bf16_f32 v8, v8, v9
	v_cvt_pk_bf16_f32 v9, v10, v11
	v_mov_b32_e32 v32, v33
	v_mov_b32_e32 v224, v8
	v_mov_b32_e32 v225, v9
	v_pk_mul_f32 v[8:9], v[34:35], v[14:15]
	v_pk_mul_f32 v[10:11], v[32:33], v[12:13]
	v_pk_fma_f32 v[0:1], v[0:1], v[8:9], v[4:5]
	v_pk_fma_f32 v[2:3], v[2:3], v[10:11], v[6:7]
	global_store_dwordx4 v[28:29], v[0:3], off offset:576 sc1
	s_nop 1
	v_cvt_pk_bf16_f32 v0, v0, v1
	v_cvt_pk_bf16_f32 v1, v2, v3
	v_mov_b32_e32 v226, v0
	v_mov_b32_e32 v227, v1
	s_nop 1
	v_permlane16_swap_b32_e32 v224, v226
	v_permlane16_swap_b32_e32 v225, v227
	s_nop 1
	global_store_dwordx4 v[30:31], v[224:227], off offset:256
